# chain: first LDS fragment reads of each step hoisted above the (scalar-base) LDS-DMA issue block; scalar-base o stores
# baseline (speedup 1.0000x reference)
; #define LAS __attribute__((address_space(3)))
; #define RD_QD(dst, s0) _Pragma("unroll") for (int s_ = 0; s_ < 4; ++s_) { dst[s_] = *(const LAS bf16x8*)(B + CH_QD + i0 * 256 + (((2 * ((s0) + s_) + hi) ^ (i0 & 15)) << 4)); \
;                 dst[4 + s_] = *(const LAS bf16x8*)(B + CH_QD + i1 * 256 + (((2 * ((s0) + s_) + hi) ^ (i1 & 15)) << 4)); }
; #define RD_KT(dst, db0) _Pragma("unroll") for (int q_ = 0; q_ < 2; ++q_) { const int d_ = ((db0) + q_) * 32 + r32; \
;                 _Pragma("unroll") for (int ks_ = 0; ks_ < 4; ++ks_) dst[q_ * 4 + ks_] = *(const LAS bf16x8*)(B + CH_KT + d_ * 128 + (((2 * ks_ + hi) ^ ((d_ >> 1) & 7)) << 4)); }
; DI void phase_gla_chain(const Params& P, int l, int task0, int ntask_stride, LAS unsigned char* lds) {
;     ...
;             const int i0 = r32, i1 = 32 + r32; const int vv = wid * 32 + r32;
;             bf16x8 fa[8], fb[8], vf[4];
;             f32x16 o[2]; for (int x = 0; x < 16; ++x) { o[0][x] = 0.f; o[1][x] = 0.f; }
;     ...
;             RD_QD(fa, 0);
; #pragma unroll
;             for (int ks = 0; ks < 4; ++ks) vf[ks] = *(const LAS bf16x8*)(B + CH_VT + vv * 128 + (((2 * ks + hi) ^ ((vv >> 1) & 7)) << 4));
;             __builtin_amdgcn_sched_barrier(0);
;             RD_QD(fb, 4);
;             __builtin_amdgcn_sched_barrier(0);
;             MM_QD(fa, 0);
;             DECAY(0); DECAY(1);
;             __builtin_amdgcn_sched_barrier(0);
; #pragma unroll
;             for (int ks = 0; ks < 4; ++ks) { fa[ks] = *(const LAS bf16x8*)(B + CH_AM + i0 * 128 + (((2 * ks + hi) ^ ((i0 >> 1) & 7)) << 4)); fa[4 + ks] = *(const LAS bf16x8*)(B + CH_AM + i1 * 128 + (((2 * ks + hi) ^ ((i1 >> 1) & 7)) << 4)); }
;             __builtin_amdgcn_sched_barrier(0);
;             MM_QD(fb, 4);
;             DECAY(2); DECAY(3);
;             __builtin_amdgcn_sched_barrier(0);
;             RD_KT(fb, 0);
;             __builtin_amdgcn_sched_barrier(0);
; #pragma unroll
;             for (int ks = 0; ks < 4; ++ks) { o[0] = __builtin_amdgcn_mfma_f32_32x32x16_bf16(fa[ks], vf[ks], o[0], 0, 0, 0); o[1] = __builtin_amdgcn_mfma_f32_32x32x16_bf16(fa[4 + ks], vf[ks], o[1], 0, 0, 0); }
;             __builtin_amdgcn_sched_barrier(0);
;             RD_KT(fa, 2);
;             __builtin_amdgcn_sched_barrier(0);
;             MM_KT(fb, 0);
;             __builtin_amdgcn_sched_barrier(0);
;             MM_KT(fa, 2);
.LBB0_409:
	s_waitcnt lgkmcnt(0)
	v_mfma_f32_32x32x16_bf16 v[82:97], v[66:69], v[74:77], 0
	v_cvt_pk_bf16_f32 v226, v14, v15
	v_cvt_pk_bf16_f32 v227, v16, v17
	v_add_u32_e32 v207, s22, v146
	v_add_u32_e32 v231, 0x12000, v207
	v_cvt_pk_bf16_f32 v228, v26, v27
	v_cvt_pk_bf16_f32 v229, v28, v29
	v_cvt_pk_bf16_f32 v230, v30, v31
	v_mfma_f32_32x32x16_bf16 v[66:81], v[70:73], v[74:77], 0
	v_mfma_f32_32x32x16_bf16 v[82:97], v[182:185], v[224:227], v[82:97]
	v_cvt_pk_bf16_f32 v182, v18, v19
	v_cvt_pk_bf16_f32 v183, v20, v21
	v_cvt_pk_bf16_f32 v184, v22, v23
	v_cvt_pk_bf16_f32 v185, v24, v25
	v_mfma_f32_32x32x16_bf16 v[66:81], v[186:189], v[224:227], v[66:81]
	ds_read_b128 v[186:189], v231 offset:64
	ds_read_b128 v[224:227], v231 offset:96
	ds_read_b128 v[232:235], v231
	ds_read_b128 v[236:239], v231 offset:32
	v_cvt_pk_bf16_f32 v231, v32, v33
	s_waitcnt lgkmcnt(0)
	v_pk_mul_f32 v[10:11], v[10:11], v[186:187]
	v_pk_mul_f32 v[12:13], v[12:13], v[188:189]
	v_pk_mul_f32 v[14:15], v[14:15], v[224:225]
	v_pk_mul_f32 v[6:7], v[6:7], v[236:237]
	v_pk_mul_f32 v[16:17], v[16:17], v[226:227]
	v_mfma_f32_32x32x16_bf16 v[82:97], v[190:193], v[182:185], v[82:97]
	v_mul_f32_e64 v8, v8, v238
	v_mul_f32_e64 v9, v9, v239
	v_mul_f32_e64 v4, v4, v234
	v_mul_f32_e64 v5, v5, v235
	v_mul_f32_e64 v2, v2, v232
	v_mul_f32_e64 v3, v3, v233
	v_mfma_f32_32x32x16_bf16 v[66:81], v[194:197], v[182:185], v[66:81]
	v_add_u32_e32 v194, 0x12080, v207
	ds_read_b128 v[182:185], v194 offset:64
	ds_read_b128 v[186:189], v194 offset:96
	ds_read_b128 v[190:193], v194
	ds_read_b128 v[194:197], v194 offset:32
	s_waitcnt lgkmcnt(0)
	v_pk_mul_f32 v[26:27], v[26:27], v[182:183]
	v_pk_mul_f32 v[30:31], v[30:31], v[186:187]
	v_pk_mul_f32 v[32:33], v[32:33], v[188:189]
	v_pk_mul_f32 v[22:23], v[22:23], v[194:195]
	v_pk_mul_f32 v[28:29], v[28:29], v[184:185]
	v_pk_mul_f32 v[24:25], v[24:25], v[196:197]
	v_pk_mul_f32 v[20:21], v[20:21], v[192:193]
	v_pk_mul_f32 v[18:19], v[18:19], v[190:191]
	v_mfma_f32_32x32x16_bf16 v[82:97], v[198:201], v[228:231], v[82:97]
	v_mfma_f32_32x32x16_bf16 v[66:81], v[208:211], v[228:231], v[66:81]
	v_add_u32_e32 v224, s22, v143
	v_add_u32_e32 v225, s22, v145
	v_add_u32_e32 v240, v224, v162
	v_add_u32_e32 v186, v225, v162
	v_add_u32_e32 v241, v224, v164
	v_add_u32_e32 v194, v225, v164
	v_add_u32_e32 v242, v224, v165
	v_add_u32_e32 v208, v225, v165
	v_add_u32_e32 v243, v224, v166
	v_add_u32_e32 v228, v225, v166
	ds_read_b128 v[182:185], v240 offset:16384
	ds_read_b128 v[186:189], v186 offset:16384
	ds_read_b128 v[190:193], v241 offset:16384
	ds_read_b128 v[194:197], v194 offset:16384
	ds_read_b128 v[198:201], v242 offset:16384
	ds_read_b128 v[208:211], v208 offset:16384
	ds_read_b128 v[224:227], v243 offset:16384
	ds_read_b128 v[228:231], v228 offset:16384
	v_cvt_pk_bf16_f32 v232, v34, v35
	v_cvt_pk_bf16_f32 v233, v36, v37
	v_cvt_pk_bf16_f32 v234, v38, v39
	v_cvt_pk_bf16_f32 v235, v40, v41
	s_nop 1
	v_mfma_f32_32x32x16_bf16 v[82:97], v[212:215], v[232:235], v[82:97]
	v_cvt_pk_bf16_f32 v212, v42, v43
	v_cvt_pk_bf16_f32 v213, v44, v45
	v_cvt_pk_bf16_f32 v214, v46, v47
	v_cvt_pk_bf16_f32 v215, v48, v49
	v_mfma_f32_32x32x16_bf16 v[66:81], v[216:219], v[232:235], v[66:81]
	v_cvt_pk_bf16_f32 v216, v50, v51
	v_cvt_pk_bf16_f32 v217, v52, v53
	v_cvt_pk_bf16_f32 v218, v54, v55
	v_cvt_pk_bf16_f32 v219, v56, v57
	v_mfma_f32_32x32x16_bf16 v[82:97], v[220:223], v[212:215], v[82:97]
	v_add_u32_e32 v223, 0x12100, v207
	v_add_u32_e32 v207, 0x12180, v207
	v_cvt_pk_bf16_f32 v220, v58, v59
	v_cvt_pk_bf16_f32 v221, v60, v61
	v_cvt_pk_bf16_f32 v222, v62, v63
	v_mfma_f32_32x32x16_bf16 v[66:81], v[130:133], v[212:215], v[66:81]
	ds_read_b128 v[130:133], v223 offset:64
	ds_read_b128 v[212:215], v223 offset:96
	ds_read_b128 v[232:235], v223
	ds_read_b128 v[236:239], v223 offset:32
	v_cvt_pk_bf16_f32 v223, v64, v65
	s_waitcnt lgkmcnt(0)
	v_pk_mul_f32 v[42:43], v[42:43], v[130:131]
	v_pk_mul_f32 v[46:47], v[46:47], v[212:213]
	v_pk_mul_f32 v[48:49], v[48:49], v[214:215]
	v_pk_mul_f32 v[44:45], v[44:45], v[132:133]
	v_pk_mul_f32 v[38:39], v[38:39], v[236:237]
	v_mfma_f32_32x32x16_bf16 v[82:97], v[126:129], v[216:219], v[82:97]
	v_mul_f32_e64 v40, v40, v238
	v_mul_f32_e64 v41, v41, v239
	v_mul_f32_e64 v36, v36, v234
	v_mul_f32_e64 v37, v37, v235
	v_mul_f32_e64 v34, v34, v232
	v_mul_f32_e64 v35, v35, v233
	v_mfma_f32_32x32x16_bf16 v[66:81], v[122:125], v[216:219], v[66:81]
	ds_read_b128 v[122:125], v207 offset:64
	ds_read_b128 v[126:129], v207 offset:96
	ds_read_b128 v[130:133], v207
	ds_read_b128 v[212:215], v207 offset:32
	s_waitcnt lgkmcnt(0)
	v_pk_mul_f32 v[58:59], v[58:59], v[122:123]
	v_pk_mul_f32 v[62:63], v[62:63], v[126:127]
	v_pk_mul_f32 v[64:65], v[64:65], v[128:129]
	v_pk_mul_f32 v[54:55], v[54:55], v[212:213]
	v_pk_mul_f32 v[60:61], v[60:61], v[124:125]
	v_pk_mul_f32 v[56:57], v[56:57], v[214:215]
	v_pk_mul_f32 v[52:53], v[52:53], v[132:133]
	v_pk_mul_f32 v[50:51], v[50:51], v[130:131]
	v_mfma_f32_32x32x16_bf16 v[82:97], v[118:121], v[220:223], v[82:97]
	v_mfma_f32_32x32x16_bf16 v[66:81], v[114:117], v[220:223], v[66:81]
	ds_read_b128 v[114:117], v240 offset:24576
	ds_read_b128 v[118:121], v240 offset:28672
	ds_read_b128 v[122:125], v241 offset:24576
	ds_read_b128 v[126:129], v241 offset:28672
	ds_read_b128 v[130:133], v242 offset:24576
	ds_read_b128 v[212:215], v242 offset:28672
	ds_read_b128 v[216:219], v243 offset:24576
	ds_read_b128 v[220:223], v243 offset:28672
	v_mfma_f32_32x32x16_bf16 v[82:97], v[182:185], v[110:113], v[82:97]
	v_mfma_f32_32x32x16_bf16 v[66:81], v[186:189], v[110:113], v[66:81]
	v_mfma_f32_32x32x16_bf16 v[82:97], v[190:193], v[106:109], v[82:97]
	v_mfma_f32_32x32x16_bf16 v[66:81], v[194:197], v[106:109], v[66:81]
	v_mfma_f32_32x32x16_bf16 v[82:97], v[198:201], v[102:105], v[82:97]
	v_mfma_f32_32x32x16_bf16 v[66:81], v[208:211], v[102:105], v[66:81]
	v_mfma_f32_32x32x16_bf16 v[82:97], v[224:227], v[98:101], v[82:97]
	v_mfma_f32_32x32x16_bf16 v[66:81], v[228:231], v[98:101], v[66:81]
	ds_read_b128 v[182:185], v240 offset:32768
	ds_read_b128 v[186:189], v240 offset:36864
	ds_read_b128 v[190:193], v241 offset:32768
	ds_read_b128 v[194:197], v241 offset:36864
	ds_read_b128 v[198:201], v242 offset:32768
	ds_read_b128 v[208:211], v242 offset:36864
	ds_read_b128 v[224:227], v243 offset:32768
	ds_read_b128 v[228:231], v243 offset:36864
	s_waitcnt lgkmcnt(0)
; DI int crow(int r, int hi) { return (r & 3) + 8 * (r >> 2) + 4 * hi; }
; DI unsigned pkbf(float a, float b) { f32x2 v = {a, b}; bfx2 r = __builtin_convertvector(v, bfx2); return __builtin_bit_cast(unsigned, r); }
; #define MM_KT(src, db0) _Pragma("unroll") for (int q_ = 0; q_ < 2; ++q_) { \
;                 _Pragma("unroll") for (int ks_ = 0; ks_ < 4; ++ks_) T[(db0) + q_] = __builtin_amdgcn_mfma_f32_32x32x16_bf16(src[q_ * 4 + ks_], vf[ks_], T[(db0) + q_], 0, 0, 0); }
; DI void phase_gla_chain(const Params& P, int l, int task0, int ntask_stride, LAS unsigned char* lds) {
;     ...
;             MM_KT(fb, 0);
;             __builtin_amdgcn_sched_barrier(0);
;             MM_KT(fa, 2);
;     ...
;             { const int cs = dir ? 63 - n : n; const size_t tokb = (size_t)sq * SEQL + cs * 64; const int odd = lane & 1;
;               bf16_t* ob = OFB + (size_t)dir * MTOK * 1024 + h * 256 + wid * 32 + (r32 & ~1);
; #pragma unroll
;               for (int ib = 0; ib < 2; ++ib)
; #pragma unroll
;                   for (int x = 0; x < 16; x += 2) { float ea_ = o[ib][x], eb_ = o[ib][x + 1]; asm volatile("" : "+v"(ea_), "+v"(eb_)); const float mine = odd ? eb_ : ea_, give = odd ? ea_ : eb_;
;                       const float got = __int_as_float(__builtin_amdgcn_update_dpp(0, __float_as_int(give), 0xB1, 0xF, 0xF, true));
;                       const unsigned w = odd ? pkbf(got, mine) : pkbf(mine, got);
;                       *(unsigned*)(ob + (tokb + ib * 32 + crow(x + odd, hi)) * 1024) = w; } }
	v_mfma_f32_32x32x16_bf16 v[2:17], v[114:117], v[110:113], v[2:17]
	v_mfma_f32_32x32x16_bf16 v[18:33], v[118:121], v[110:113], v[18:33]
	v_mfma_f32_32x32x16_bf16 v[2:17], v[122:125], v[106:109], v[2:17]
	v_mfma_f32_32x32x16_bf16 v[18:33], v[126:129], v[106:109], v[18:33]
	v_mfma_f32_32x32x16_bf16 v[2:17], v[130:133], v[102:105], v[2:17]
	v_mfma_f32_32x32x16_bf16 v[18:33], v[212:215], v[102:105], v[18:33]
	v_mfma_f32_32x32x16_bf16 v[2:17], v[216:219], v[98:101], v[2:17]
	v_mfma_f32_32x32x16_bf16 v[18:33], v[220:223], v[98:101], v[18:33]
	s_add_i32 s64, s8, 1
	s_and_b64 s[22:23], s[10:11], exec
	s_cselect_b32 s22, s91, s64
	s_lshl_b32 s22, s22, 6
	s_add_u32 s23, s20, s22
	v_cndmask_b32_e64 v114, v82, v83, s[0:1]
	s_addc_u32 s22, s21, 0
	v_mfma_f32_32x32x16_bf16 v[34:49], v[182:185], v[110:113], v[34:49]
	v_mov_b32_dpp v114, v114 quad_perm:[1,0,3,2] row_mask:0xf bank_mask:0xf bound_ctrl:1
	v_cndmask_b32_e64 v83, v83, v114, s[0:1]
	v_cndmask_b32_e64 v82, v114, v82, s[0:1]
	v_cvt_pk_bf16_f32 v114, v82, v83
	v_readfirstlane_b32 s98, v158
	v_readfirstlane_b32 s99, v159
	v_and_b32_e32 v244, 30, v137
	v_lshlrev_b32_e32 v244, 1, v244
	v_lshl_add_u32 v244, v136, 11, v244
	s_lshl_b32 s100, s23, 11
	s_add_u32 s98, s98, s100
	s_addc_u32 s99, s99, 0
	s_add_u32 s100, s98, 0x800
	s_addc_u32 s101, s99, 0
	global_store_dword v244, v114, s[100:101] offset:-2048
	v_mov_b32_e32 v82, v84
	v_mfma_f32_32x32x16_bf16 v[50:65], v[186:189], v[110:113], v[50:65]
	v_cndmask_b32_e64 v83, v82, v85, s[0:1]
	s_add_i32 s8, s8, -1
	s_add_i32 s90, s90, 1
	v_mov_b32_dpp v83, v83 quad_perm:[1,0,3,2] row_mask:0xf bank_mask:0xf bound_ctrl:1
	v_cndmask_b32_e64 v84, v85, v83, s[0:1]
	v_cndmask_b32_e64 v82, v83, v82, s[0:1]
	v_cvt_pk_bf16_f32 v84, v82, v84
	global_store_dword v244, v84, s[100:101] offset:2048
	v_mov_b32_e32 v82, v87
	v_mfma_f32_32x32x16_bf16 v[34:49], v[190:193], v[106:109], v[34:49]
	v_cndmask_b32_e64 v83, v86, v82, s[0:1]
	s_nop 1
	v_mov_b32_dpp v83, v83 quad_perm:[1,0,3,2] row_mask:0xf bank_mask:0xf bound_ctrl:1
	v_cndmask_b32_e64 v82, v82, v83, s[0:1]
	v_cndmask_b32_e64 v83, v83, v86, s[0:1]
	v_cvt_pk_bf16_f32 v84, v83, v82
	s_add_u32 s100, s98, 0x4800
	s_addc_u32 s101, s99, 0
	global_store_dword v244, v84, s[100:101] offset:-2048
	v_mov_b32_e32 v82, v88
	v_mfma_f32_32x32x16_bf16 v[50:65], v[194:197], v[106:109], v[50:65]
	v_cndmask_b32_e64 v83, v82, v89, s[0:1]
	s_nop 1
	v_mov_b32_dpp v83, v83 quad_perm:[1,0,3,2] row_mask:0xf bank_mask:0xf bound_ctrl:1
	v_cndmask_b32_e64 v84, v89, v83, s[0:1]
	v_cndmask_b32_e64 v82, v83, v82, s[0:1]
	v_cvt_pk_bf16_f32 v84, v82, v84
	global_store_dword v244, v84, s[100:101] offset:2048
	v_mov_b32_e32 v82, v90
	v_mfma_f32_32x32x16_bf16 v[34:49], v[198:201], v[102:105], v[34:49]
	v_cndmask_b32_e64 v83, v82, v91, s[0:1]
	s_nop 1
	v_mov_b32_dpp v83, v83 quad_perm:[1,0,3,2] row_mask:0xf bank_mask:0xf bound_ctrl:1
	v_cndmask_b32_e64 v84, v91, v83, s[0:1]
	v_cndmask_b32_e64 v82, v83, v82, s[0:1]
	v_cvt_pk_bf16_f32 v84, v82, v84
	s_add_u32 s100, s98, 0x8800
	s_addc_u32 s101, s99, 0
	global_store_dword v244, v84, s[100:101] offset:-2048
	v_mov_b32_e32 v82, v93
	v_mfma_f32_32x32x16_bf16 v[50:65], v[208:211], v[102:105], v[50:65]
	v_cndmask_b32_e64 v83, v92, v82, s[0:1]
	s_nop 1
	v_mov_b32_dpp v83, v83 quad_perm:[1,0,3,2] row_mask:0xf bank_mask:0xf bound_ctrl:1
	v_cndmask_b32_e64 v82, v82, v83, s[0:1]
	v_cndmask_b32_e64 v83, v83, v92, s[0:1]
	v_cvt_pk_bf16_f32 v84, v83, v82
	global_store_dword v244, v84, s[100:101] offset:2048
	v_mov_b32_e32 v82, v94
	v_mfma_f32_32x32x16_bf16 v[34:49], v[224:227], v[98:101], v[34:49]
	v_cndmask_b32_e64 v83, v82, v95, s[0:1]
	s_nop 1
	v_mov_b32_dpp v83, v83 quad_perm:[1,0,3,2] row_mask:0xf bank_mask:0xf bound_ctrl:1
	v_cndmask_b32_e64 v84, v95, v83, s[0:1]
	v_cndmask_b32_e64 v82, v83, v82, s[0:1]
	v_cvt_pk_bf16_f32 v84, v82, v84
	s_add_u32 s100, s98, 0xc800
	s_addc_u32 s101, s99, 0
	global_store_dword v244, v84, s[100:101] offset:-2048
	v_mov_b32_e32 v82, v96
	v_mfma_f32_32x32x16_bf16 v[50:65], v[228:231], v[98:101], v[50:65]
	v_cndmask_b32_e64 v83, v82, v97, s[0:1]
	s_nop 1
	v_mov_b32_dpp v83, v83 quad_perm:[1,0,3,2] row_mask:0xf bank_mask:0xf bound_ctrl:1
	v_cndmask_b32_e64 v84, v97, v83, s[0:1]
	v_cndmask_b32_e64 v82, v83, v82, s[0:1]
	v_cvt_pk_bf16_f32 v84, v82, v84
	global_store_dword v244, v84, s[100:101] offset:2048
	s_or_b32 s23, s23, 32
	v_cndmask_b32_e64 v82, v66, v67, s[0:1]
	s_nop 0
	v_mov_b32_dpp v82, v82 quad_perm:[1,0,3,2] row_mask:0xf bank_mask:0xf bound_ctrl:1
	v_cndmask_b32_e64 v67, v67, v82, s[0:1]
	v_cndmask_b32_e64 v66, v82, v66, s[0:1]
	v_cvt_pk_bf16_f32 v82, v66, v67
	s_add_u32 s100, s98, 0x10800
	s_addc_u32 s101, s99, 0
	global_store_dword v244, v82, s[100:101] offset:-2048
	v_mov_b32_e32 v66, v68
	s_nop 0
	v_cndmask_b32_e64 v67, v66, v69, s[0:1]
	s_nop 1
	v_mov_b32_dpp v67, v67 quad_perm:[1,0,3,2] row_mask:0xf bank_mask:0xf bound_ctrl:1
	v_cndmask_b32_e64 v68, v69, v67, s[0:1]
	v_cndmask_b32_e64 v66, v67, v66, s[0:1]
	v_cvt_pk_bf16_f32 v68, v66, v68
	global_store_dword v244, v68, s[100:101] offset:2048
	v_mov_b32_e32 v66, v70
	s_nop 0
	v_cndmask_b32_e64 v67, v66, v71, s[0:1]
	s_nop 1
	v_mov_b32_dpp v67, v67 quad_perm:[1,0,3,2] row_mask:0xf bank_mask:0xf bound_ctrl:1
	v_cndmask_b32_e64 v68, v71, v67, s[0:1]
	v_cndmask_b32_e64 v66, v67, v66, s[0:1]
	v_cvt_pk_bf16_f32 v68, v66, v68
	s_add_u32 s100, s98, 0x14800
	s_addc_u32 s101, s99, 0
	global_store_dword v244, v68, s[100:101] offset:-2048
	v_mov_b32_e32 v66, v73
; #define LAS __attribute__((address_space(3)))
; DI int crow(int r, int hi) { return (r & 3) + 8 * (r >> 2) + 4 * hi; }
; DI unsigned pkbf(float a, float b) { f32x2 v = {a, b}; bfx2 r = __builtin_convertvector(v, bfx2); return __builtin_bit_cast(unsigned, r); }
; DI void phase_gla_chain(const Params& P, int l, int task0, int ntask_stride, LAS unsigned char* lds) {
;     ...
;         __syncthreads();
;         CH_ISSUE(0, 0);
;         for (int n = 0; n < 64; ++n) {
;             const int b = n & 1;
;             if (n == 0) asm volatile("s_waitcnt vmcnt(0)" ::: "memory"); else asm volatile("s_waitcnt vmcnt(16)" ::: "memory");
;             __builtin_amdgcn_s_barrier();
;             asm volatile("" ::: "memory");
;             if (n + 1 < 64) CH_ISSUE(n + 1, b ^ 1);
;             const LAS unsigned char* B = lds + b * CH_BUF;
;             const int i0 = r32, i1 = 32 + r32; const int vv = wid * 32 + r32;
;             bf16x8 fa[8], fb[8], vf[4];
;             f32x16 o[2]; for (int x = 0; x < 16; ++x) { o[0][x] = 0.f; o[1][x] = 0.f; }
;     ...
;             RD_QD(fa, 0);
; #pragma unroll
;             for (int ks = 0; ks < 4; ++ks) vf[ks] = *(const LAS bf16x8*)(B + CH_VT + vv * 128 + (((2 * ks + hi) ^ ((vv >> 1) & 7)) << 4));
;             __builtin_amdgcn_sched_barrier(0);
;             RD_QD(fb, 4);
;     ...
;             { const int cs = dir ? 63 - n : n; const size_t tokb = (size_t)sq * SEQL + cs * 64; const int odd = lane & 1;
;               bf16_t* ob = OFB + (size_t)dir * MTOK * 1024 + h * 256 + wid * 32 + (r32 & ~1);
; #pragma unroll
;               for (int ib = 0; ib < 2; ++ib)
; #pragma unroll
;                   for (int x = 0; x < 16; x += 2) { float ea_ = o[ib][x], eb_ = o[ib][x + 1]; asm volatile("" : "+v"(ea_), "+v"(eb_)); const float mine = odd ? eb_ : ea_, give = odd ? ea_ : eb_;
;                       const float got = __int_as_float(__builtin_amdgcn_update_dpp(0, __float_as_int(give), 0xB1, 0xF, 0xF, true));
;                       const unsigned w = odd ? pkbf(got, mine) : pkbf(mine, got);
;                       *(unsigned*)(ob + (tokb + ib * 32 + crow(x + odd, hi)) * 1024) = w; } }
	s_nop 0
	v_cndmask_b32_e64 v67, v72, v66, s[0:1]
	s_nop 1
	v_mov_b32_dpp v67, v67 quad_perm:[1,0,3,2] row_mask:0xf bank_mask:0xf bound_ctrl:1
	v_cndmask_b32_e64 v66, v66, v67, s[0:1]
	v_cndmask_b32_e64 v67, v67, v72, s[0:1]
	v_cvt_pk_bf16_f32 v68, v67, v66
	global_store_dword v244, v68, s[100:101] offset:2048
	v_mov_b32_e32 v66, v74
	s_nop 0
	v_cndmask_b32_e64 v67, v66, v75, s[0:1]
	s_nop 1
	v_mov_b32_dpp v67, v67 quad_perm:[1,0,3,2] row_mask:0xf bank_mask:0xf bound_ctrl:1
	v_cndmask_b32_e64 v68, v75, v67, s[0:1]
	v_cndmask_b32_e64 v66, v67, v66, s[0:1]
	v_cvt_pk_bf16_f32 v68, v66, v68
	s_add_u32 s100, s98, 0x18800
	s_addc_u32 s101, s99, 0
	global_store_dword v244, v68, s[100:101] offset:-2048
	v_mov_b32_e32 v66, v76
	s_nop 0
	v_cndmask_b32_e64 v67, v66, v77, s[0:1]
	s_nop 1
	v_mov_b32_dpp v67, v67 quad_perm:[1,0,3,2] row_mask:0xf bank_mask:0xf bound_ctrl:1
	v_cndmask_b32_e64 v68, v77, v67, s[0:1]
	v_cndmask_b32_e64 v66, v67, v66, s[0:1]
	v_cvt_pk_bf16_f32 v68, v66, v68
	global_store_dword v244, v68, s[100:101] offset:2048
	v_mov_b32_e32 v66, v79
	s_nop 0
	v_cndmask_b32_e64 v67, v78, v66, s[0:1]
	s_nop 1
	v_mov_b32_dpp v67, v67 quad_perm:[1,0,3,2] row_mask:0xf bank_mask:0xf bound_ctrl:1
	v_cndmask_b32_e64 v66, v66, v67, s[0:1]
	v_cndmask_b32_e64 v67, v67, v78, s[0:1]
	v_cvt_pk_bf16_f32 v68, v67, v66
	s_add_u32 s100, s98, 0x1c800
	s_addc_u32 s101, s99, 0
	global_store_dword v244, v68, s[100:101] offset:-2048
	v_mov_b32_e32 v66, v81
	s_nop 0
	v_cndmask_b32_e64 v67, v80, v66, s[0:1]
	s_nop 1
	v_mov_b32_dpp v67, v67 quad_perm:[1,0,3,2] row_mask:0xf bank_mask:0xf bound_ctrl:1
	v_cndmask_b32_e64 v66, v66, v67, s[0:1]
	v_cndmask_b32_e64 v67, v67, v80, s[0:1]
	v_cvt_pk_bf16_f32 v68, v67, v66
	global_store_dword v244, v68, s[100:101] offset:2048
	s_cmp_eq_u32 s8, -2
	s_cbranch_scc1 .LBB0_403
.LBB0_410:
	s_add_i32 s91, s90, -1
	s_waitcnt vmcnt(16)
	s_barrier
	s_and_b32 s92, s91, 1
	s_mul_i32 s92, s92, 0x12400
	s_add_i32 s22, s92, 0
	v_add_u32_e32 v74, s22, v205
	v_add_u32_e32 v75, s22, v141
	v_add_u32_e32 v66, v74, v149
	v_add_u32_e32 v70, v75, v149
	v_add_u32_e32 v76, v74, v151
	ds_read_b128 v[66:69], v66
	ds_read_b128 v[70:73], v70
	v_add_u32_e32 v77, v75, v151
	ds_read_b128 v[182:185], v76
	ds_read_b128 v[186:189], v77
	v_add_u32_e32 v76, v74, v153
	v_add_u32_e32 v77, v75, v153
	ds_read_b128 v[190:193], v76
	ds_read_b128 v[194:197], v77
	v_add_u32_e32 v76, v74, v160
	v_add_u32_e32 v77, v75, v160
	ds_read_b128 v[198:201], v76
	ds_read_b128 v[208:211], v77
	v_add_u32_e32 v76, s22, v173
	v_add_u32_e32 v77, v76, v162
	v_add_u32_e32 v78, v76, v164
	ds_read_b128 v[110:113], v77 offset:40960
	ds_read_b128 v[106:109], v78 offset:40960
	v_add_u32_e32 v77, v76, v165
	v_add_u32_e32 v76, v76, v166
	ds_read_b128 v[102:105], v77 offset:40960
	ds_read_b128 v[98:101], v76 offset:40960
	v_add_u32_e32 v76, v74, v167
	v_add_u32_e32 v77, v75, v167
	ds_read_b128 v[212:215], v76
	ds_read_b128 v[216:219], v77
	v_add_u32_e32 v76, v74, v168
	v_add_u32_e32 v77, v75, v168
	ds_read_b128 v[220:223], v76
	ds_read_b128 v[130:133], v77
	v_add_u32_e32 v76, v74, v169
	v_add_u32_e32 v74, v74, v170
	v_add_u32_e32 v77, v75, v169
	ds_read_b128 v[126:129], v76
	ds_read_b128 v[122:125], v77
	v_add_u32_e32 v75, v75, v170
	ds_read_b128 v[118:121], v74
	ds_read_b128 v[114:117], v75
	v_cvt_pk_bf16_f32 v74, v2, v3
	v_cvt_pk_bf16_f32 v75, v4, v5
	v_cvt_pk_bf16_f32 v76, v6, v7
	v_cvt_pk_bf16_f32 v77, v8, v9
	v_cvt_pk_bf16_f32 v224, v10, v11
	v_cvt_pk_bf16_f32 v225, v12, v13
	s_cmp_eq_u32 s8, -1
	s_cbranch_scc1 .LBB0_409
	s_and_b64 s[22:23], s[10:11], exec
	s_cselect_b32 s22, s90, s8
	s_add_i32 s22, s22, s89
	s_lshl_b32 s22, s22, 2
	s_or_b32 s96, s22, s88
	s_ashr_i32 s97, s96, 31
	s_add_u32 s22, s25, s96
	s_addc_u32 s23, 0, s97
	s_mul_i32 s93, s23, 0xa000
	s_mul_hi_u32 vcc_lo, s22, 0xa000
	s_add_i32 vcc_lo, vcc_lo, s93
	s_mul_i32 s93, s22, 0xa000
	s_add_u32 vcc_hi, s27, s93
	s_addc_u32 vcc_lo, s28, vcc_lo
	s_lshl_b64 s[96:97], s[96:97], 15
	s_add_u32 s68, s29, s96
	s_addc_u32 s69, s30, s97
	s_sub_i32 s93, 0x12400, s92
	s_add_i32 s93, s93, 0
	v_add_u32_e32 v245, 0x400, v134
	v_add_u32_e32 v246, 0x800, v134
	v_add_u32_e32 v247, 0xc00, v134
	v_add_u32_e32 v248, 0x1000, v134
	s_lshl_b32 s32, s31, 4
	s_lshl_b32 s98, s31, 2
	s_add_i32 s98, s98, s32
	s_add_u32 s100, vcc_hi, s98
	s_addc_u32 s101, vcc_lo, 0
	s_add_i32 s99, s93, s98
	s_add_i32 m0, s99, 0x0
	s_nop 0
	global_load_lds_dwordx4 v134, s[100:101] nt
	s_add_i32 m0, s99, 0x400
	s_nop 0
	global_load_lds_dwordx4 v245, s[100:101] nt
	s_add_i32 m0, s99, 0x800
	s_nop 0
	global_load_lds_dwordx4 v246, s[100:101] nt
	s_add_i32 m0, s99, 0xc00
	s_nop 0
	global_load_lds_dwordx4 v247, s[100:101] nt
	s_add_i32 m0, s99, 0x1000
	s_nop 0
	global_load_lds_dwordx4 v248, s[100:101] nt
	s_add_u32 s100, s68, s32
	s_addc_u32 s101, s69, 0
	s_add_i32 s99, s93, s32
	s_add_i32 m0, s99, 0xa000
	s_nop 0
	global_load_lds_dwordx4 v134, s[100:101] nt
	s_add_i32 m0, s99, 0xa400
	s_nop 0
	global_load_lds_dwordx4 v245, s[100:101] nt
	s_add_i32 m0, s99, 0xa800
	s_nop 0
	global_load_lds_dwordx4 v246, s[100:101] nt
	s_add_i32 m0, s99, 0xac00
	s_nop 0
	global_load_lds_dwordx4 v247, s[100:101] nt
	s_cmp_lg_u64 s[2:3], 0
	s_cbranch_scc1 .Lchain_nodec_0
	s_lshl_b64 s[100:101], s[22:23], 9
	s_add_i32 s98, s93, s31
	s_add_i32 m0, s98, 0x12000
	v_lshl_add_u64 v[250:251], v[156:157], 0, s[100:101]
	global_load_lds_dword v[250:251], off
.Lchain_nodec_0:
	s_add_i32 s22, s92, 0
	s_branch .LBB0_409

; #define LAS __attribute__((address_space(3)))
; #define RD_QD(dst, s0) _Pragma("unroll") for (int s_ = 0; s_ < 4; ++s_) { dst[s_] = *(const LAS bf16x8*)(B + CH_QD + i0 * 256 + (((2 * ((s0) + s_) + hi) ^ (i0 & 15)) << 4)); \
;                 dst[4 + s_] = *(const LAS bf16x8*)(B + CH_QD + i1 * 256 + (((2 * ((s0) + s_) + hi) ^ (i1 & 15)) << 4)); }
; #define RD_KT(dst, db0) _Pragma("unroll") for (int q_ = 0; q_ < 2; ++q_) { const int d_ = ((db0) + q_) * 32 + r32; \
;                 _Pragma("unroll") for (int ks_ = 0; ks_ < 4; ++ks_) dst[q_ * 4 + ks_] = *(const LAS bf16x8*)(B + CH_KT + d_ * 128 + (((2 * ks_ + hi) ^ ((d_ >> 1) & 7)) << 4)); }
; DI void phase_gla_chain(const Params& P, int l, int task0, int ntask_stride, LAS unsigned char* lds) {
;     ...
;             const int i0 = r32, i1 = 32 + r32; const int vv = wid * 32 + r32;
;             bf16x8 fa[8], fb[8], vf[4];
;             f32x16 o[2]; for (int x = 0; x < 16; ++x) { o[0][x] = 0.f; o[1][x] = 0.f; }
;     ...
;             RD_QD(fa, 0);
; #pragma unroll
;             for (int ks = 0; ks < 4; ++ks) vf[ks] = *(const LAS bf16x8*)(B + CH_VT + vv * 128 + (((2 * ks + hi) ^ ((vv >> 1) & 7)) << 4));
;             __builtin_amdgcn_sched_barrier(0);
;             RD_QD(fb, 4);
;             __builtin_amdgcn_sched_barrier(0);
;             MM_QD(fa, 0);
;             DECAY(0); DECAY(1);
;             __builtin_amdgcn_sched_barrier(0);
; #pragma unroll
;             for (int ks = 0; ks < 4; ++ks) { fa[ks] = *(const LAS bf16x8*)(B + CH_AM + i0 * 128 + (((2 * ks + hi) ^ ((i0 >> 1) & 7)) << 4)); fa[4 + ks] = *(const LAS bf16x8*)(B + CH_AM + i1 * 128 + (((2 * ks + hi) ^ ((i1 >> 1) & 7)) << 4)); }
;             __builtin_amdgcn_sched_barrier(0);
;             MM_QD(fb, 4);
;             DECAY(2); DECAY(3);
;             __builtin_amdgcn_sched_barrier(0);
;             RD_KT(fb, 0);
;             __builtin_amdgcn_sched_barrier(0);
; #pragma unroll
;             for (int ks = 0; ks < 4; ++ks) { o[0] = __builtin_amdgcn_mfma_f32_32x32x16_bf16(fa[ks], vf[ks], o[0], 0, 0, 0); o[1] = __builtin_amdgcn_mfma_f32_32x32x16_bf16(fa[4 + ks], vf[ks], o[1], 0, 0, 0); }
;             __builtin_amdgcn_sched_barrier(0);
;             RD_KT(fa, 2);
;             __builtin_amdgcn_sched_barrier(0);
;             MM_KT(fb, 0);
;             __builtin_amdgcn_sched_barrier(0);
;             MM_KT(fa, 2);
.LBB0_971:
	s_waitcnt lgkmcnt(0)
	v_mfma_f32_32x32x16_bf16 v[82:97], v[66:69], v[74:77], 0
	v_cvt_pk_bf16_f32 v226, v14, v15
	v_cvt_pk_bf16_f32 v227, v16, v17
	v_add_u32_e32 v198, s22, v146
	v_add_u32_e32 v199, 0x12000, v198
	v_cvt_pk_bf16_f32 v228, v26, v27
	v_cvt_pk_bf16_f32 v229, v28, v29
	v_cvt_pk_bf16_f32 v230, v30, v31
	v_mfma_f32_32x32x16_bf16 v[66:81], v[70:73], v[74:77], 0
	v_cvt_pk_bf16_f32 v231, v32, v33
	v_mfma_f32_32x32x16_bf16 v[82:97], v[182:185], v[224:227], v[82:97]
	v_cvt_pk_bf16_f32 v182, v18, v19
	v_cvt_pk_bf16_f32 v183, v20, v21
	v_cvt_pk_bf16_f32 v184, v22, v23
	v_cvt_pk_bf16_f32 v185, v24, v25
	v_mfma_f32_32x32x16_bf16 v[66:81], v[186:189], v[224:227], v[66:81]
	ds_read_b128 v[186:189], v199 offset:64
	ds_read_b128 v[224:227], v199 offset:96
	ds_read_b128 v[232:235], v199
	ds_read_b128 v[236:239], v199 offset:32
	s_waitcnt lgkmcnt(0)
	v_pk_mul_f32 v[10:11], v[10:11], v[186:187]
	v_pk_mul_f32 v[12:13], v[12:13], v[188:189]
	v_pk_mul_f32 v[14:15], v[14:15], v[224:225]
	v_pk_mul_f32 v[6:7], v[6:7], v[236:237]
	v_pk_mul_f32 v[16:17], v[16:17], v[226:227]
	v_mfma_f32_32x32x16_bf16 v[82:97], v[190:193], v[182:185], v[82:97]
	v_mul_f32_e64 v8, v8, v238
	v_mul_f32_e64 v9, v9, v239
	v_mul_f32_e64 v4, v4, v234
	v_mul_f32_e64 v5, v5, v235
	v_mul_f32_e64 v2, v2, v232
	v_mul_f32_e64 v3, v3, v233
	v_mfma_f32_32x32x16_bf16 v[66:81], v[194:197], v[182:185], v[66:81]
	v_add_u32_e32 v194, 0x12080, v198
	ds_read_b128 v[182:185], v194 offset:64
	ds_read_b128 v[186:189], v194 offset:96
	ds_read_b128 v[190:193], v194
	ds_read_b128 v[194:197], v194 offset:32
	s_waitcnt lgkmcnt(0)
	v_pk_mul_f32 v[26:27], v[26:27], v[182:183]
	v_pk_mul_f32 v[30:31], v[30:31], v[186:187]
	v_pk_mul_f32 v[32:33], v[32:33], v[188:189]
	v_pk_mul_f32 v[22:23], v[22:23], v[194:195]
	v_pk_mul_f32 v[28:29], v[28:29], v[184:185]
	v_pk_mul_f32 v[24:25], v[24:25], v[196:197]
	v_pk_mul_f32 v[20:21], v[20:21], v[192:193]
	v_pk_mul_f32 v[18:19], v[18:19], v[190:191]
	v_mfma_f32_32x32x16_bf16 v[82:97], v[204:207], v[228:231], v[82:97]
	v_mfma_f32_32x32x16_bf16 v[66:81], v[208:211], v[228:231], v[66:81]
	v_add_u32_e32 v199, s22, v143
	v_add_u32_e32 v224, s22, v145
	v_add_u32_e32 v240, v199, v162
	v_add_u32_e32 v186, v224, v162
	v_add_u32_e32 v241, v199, v164
	v_add_u32_e32 v194, v224, v164
	v_add_u32_e32 v242, v199, v165
	v_add_u32_e32 v208, v224, v165
	v_add_u32_e32 v199, v199, v166
	v_add_u32_e32 v228, v224, v166
	ds_read_b128 v[182:185], v240 offset:16384
	ds_read_b128 v[186:189], v186 offset:16384
	ds_read_b128 v[190:193], v241 offset:16384
	ds_read_b128 v[194:197], v194 offset:16384
	ds_read_b128 v[204:207], v242 offset:16384
	ds_read_b128 v[208:211], v208 offset:16384
	ds_read_b128 v[224:227], v199 offset:16384
	ds_read_b128 v[228:231], v228 offset:16384
	v_cvt_pk_bf16_f32 v232, v34, v35
	v_cvt_pk_bf16_f32 v233, v36, v37
	v_cvt_pk_bf16_f32 v234, v38, v39
	v_cvt_pk_bf16_f32 v235, v40, v41
	s_nop 1
	v_mfma_f32_32x32x16_bf16 v[82:97], v[212:215], v[232:235], v[82:97]
	v_cvt_pk_bf16_f32 v212, v42, v43
	v_cvt_pk_bf16_f32 v213, v44, v45
	v_cvt_pk_bf16_f32 v214, v46, v47
	v_cvt_pk_bf16_f32 v215, v48, v49
	v_mfma_f32_32x32x16_bf16 v[66:81], v[216:219], v[232:235], v[66:81]
	v_cvt_pk_bf16_f32 v216, v50, v51
	v_cvt_pk_bf16_f32 v217, v52, v53
	v_cvt_pk_bf16_f32 v218, v54, v55
	v_cvt_pk_bf16_f32 v219, v56, v57
	v_mfma_f32_32x32x16_bf16 v[82:97], v[220:223], v[212:215], v[82:97]
	v_add_u32_e32 v223, 0x12100, v198
	v_add_u32_e32 v198, 0x12180, v198
	v_cvt_pk_bf16_f32 v220, v58, v59
	v_cvt_pk_bf16_f32 v221, v60, v61
	v_cvt_pk_bf16_f32 v222, v62, v63
	v_mfma_f32_32x32x16_bf16 v[66:81], v[130:133], v[212:215], v[66:81]
	ds_read_b128 v[130:133], v223 offset:64
	ds_read_b128 v[212:215], v223 offset:96
	ds_read_b128 v[232:235], v223
	ds_read_b128 v[236:239], v223 offset:32
	v_cvt_pk_bf16_f32 v223, v64, v65
	s_waitcnt lgkmcnt(0)
	v_pk_mul_f32 v[42:43], v[42:43], v[130:131]
	v_pk_mul_f32 v[46:47], v[46:47], v[212:213]
	v_pk_mul_f32 v[48:49], v[48:49], v[214:215]
	v_pk_mul_f32 v[44:45], v[44:45], v[132:133]
	v_pk_mul_f32 v[38:39], v[38:39], v[236:237]
	v_mfma_f32_32x32x16_bf16 v[82:97], v[126:129], v[216:219], v[82:97]
	v_mul_f32_e64 v40, v40, v238
	v_mul_f32_e64 v41, v41, v239
	v_mul_f32_e64 v36, v36, v234
	v_mul_f32_e64 v37, v37, v235
	v_mul_f32_e64 v34, v34, v232
	v_mul_f32_e64 v35, v35, v233
	v_mfma_f32_32x32x16_bf16 v[66:81], v[122:125], v[216:219], v[66:81]
	ds_read_b128 v[122:125], v198 offset:64
	ds_read_b128 v[126:129], v198 offset:96
	ds_read_b128 v[130:133], v198
	ds_read_b128 v[212:215], v198 offset:32
	s_waitcnt lgkmcnt(0)
	v_pk_mul_f32 v[58:59], v[58:59], v[122:123]
	v_pk_mul_f32 v[62:63], v[62:63], v[126:127]
	v_pk_mul_f32 v[64:65], v[64:65], v[128:129]
	v_pk_mul_f32 v[54:55], v[54:55], v[212:213]
	v_pk_mul_f32 v[60:61], v[60:61], v[124:125]
	v_pk_mul_f32 v[56:57], v[56:57], v[214:215]
	v_pk_mul_f32 v[52:53], v[52:53], v[132:133]
	v_pk_mul_f32 v[50:51], v[50:51], v[130:131]
	v_mfma_f32_32x32x16_bf16 v[82:97], v[118:121], v[220:223], v[82:97]
	v_mfma_f32_32x32x16_bf16 v[66:81], v[114:117], v[220:223], v[66:81]
	ds_read_b128 v[114:117], v240 offset:24576
	ds_read_b128 v[118:121], v240 offset:28672
	ds_read_b128 v[122:125], v241 offset:24576
	ds_read_b128 v[126:129], v241 offset:28672
	ds_read_b128 v[130:133], v242 offset:24576
	ds_read_b128 v[212:215], v242 offset:28672
	ds_read_b128 v[216:219], v199 offset:24576
	ds_read_b128 v[220:223], v199 offset:28672
	v_mfma_f32_32x32x16_bf16 v[82:97], v[182:185], v[110:113], v[82:97]
	v_mfma_f32_32x32x16_bf16 v[66:81], v[186:189], v[110:113], v[66:81]
	v_mfma_f32_32x32x16_bf16 v[82:97], v[190:193], v[106:109], v[82:97]
	v_mfma_f32_32x32x16_bf16 v[66:81], v[194:197], v[106:109], v[66:81]
	v_mfma_f32_32x32x16_bf16 v[82:97], v[204:207], v[102:105], v[82:97]
	v_mfma_f32_32x32x16_bf16 v[66:81], v[208:211], v[102:105], v[66:81]
	v_mfma_f32_32x32x16_bf16 v[82:97], v[224:227], v[98:101], v[82:97]
	v_mfma_f32_32x32x16_bf16 v[66:81], v[228:231], v[98:101], v[66:81]
	ds_read_b128 v[182:185], v240 offset:32768
	ds_read_b128 v[186:189], v240 offset:36864
	ds_read_b128 v[190:193], v241 offset:32768
	ds_read_b128 v[194:197], v241 offset:36864
	ds_read_b128 v[204:207], v242 offset:32768
	ds_read_b128 v[208:211], v242 offset:36864
	ds_read_b128 v[224:227], v199 offset:32768
	ds_read_b128 v[228:231], v199 offset:36864
	s_waitcnt lgkmcnt(0)
; DI int crow(int r, int hi) { return (r & 3) + 8 * (r >> 2) + 4 * hi; }
; DI unsigned pkbf(float a, float b) { f32x2 v = {a, b}; bfx2 r = __builtin_convertvector(v, bfx2); return __builtin_bit_cast(unsigned, r); }
; #define MM_KT(src, db0) _Pragma("unroll") for (int q_ = 0; q_ < 2; ++q_) { \
;                 _Pragma("unroll") for (int ks_ = 0; ks_ < 4; ++ks_) T[(db0) + q_] = __builtin_amdgcn_mfma_f32_32x32x16_bf16(src[q_ * 4 + ks_], vf[ks_], T[(db0) + q_], 0, 0, 0); }
; DI void phase_gla_chain(const Params& P, int l, int task0, int ntask_stride, LAS unsigned char* lds) {
;     ...
;             MM_KT(fb, 0);
;             __builtin_amdgcn_sched_barrier(0);
;             MM_KT(fa, 2);
;     ...
;             { const int cs = dir ? 63 - n : n; const size_t tokb = (size_t)sq * SEQL + cs * 64; const int odd = lane & 1;
;               bf16_t* ob = OFB + (size_t)dir * MTOK * 1024 + h * 256 + wid * 32 + (r32 & ~1);
; #pragma unroll
;               for (int ib = 0; ib < 2; ++ib)
; #pragma unroll
;                   for (int x = 0; x < 16; x += 2) { float ea_ = o[ib][x], eb_ = o[ib][x + 1]; asm volatile("" : "+v"(ea_), "+v"(eb_)); const float mine = odd ? eb_ : ea_, give = odd ? ea_ : eb_;
;                       const float got = __int_as_float(__builtin_amdgcn_update_dpp(0, __float_as_int(give), 0xB1, 0xF, 0xF, true));
;                       const unsigned w = odd ? pkbf(got, mine) : pkbf(mine, got);
;                       *(unsigned*)(ob + (tokb + ib * 32 + crow(x + odd, hi)) * 1024) = w; } }
	v_mfma_f32_32x32x16_bf16 v[2:17], v[114:117], v[110:113], v[2:17]
	v_mfma_f32_32x32x16_bf16 v[18:33], v[118:121], v[110:113], v[18:33]
	v_mfma_f32_32x32x16_bf16 v[2:17], v[122:125], v[106:109], v[2:17]
	v_mfma_f32_32x32x16_bf16 v[18:33], v[126:129], v[106:109], v[18:33]
	v_mfma_f32_32x32x16_bf16 v[2:17], v[130:133], v[102:105], v[2:17]
	v_mfma_f32_32x32x16_bf16 v[18:33], v[212:215], v[102:105], v[18:33]
	v_mfma_f32_32x32x16_bf16 v[2:17], v[216:219], v[98:101], v[2:17]
	v_mfma_f32_32x32x16_bf16 v[18:33], v[220:223], v[98:101], v[18:33]
	s_add_i32 s64, s8, 1
	s_and_b64 s[22:23], s[10:11], exec
	s_cselect_b32 s22, s83, s64
	s_lshl_b32 s22, s22, 6
	s_add_u32 s23, s20, s22
	v_cndmask_b32_e64 v114, v82, v83, s[0:1]
	s_addc_u32 s22, s21, 0
	v_mfma_f32_32x32x16_bf16 v[34:49], v[182:185], v[110:113], v[34:49]
	v_mov_b32_dpp v114, v114 quad_perm:[1,0,3,2] row_mask:0xf bank_mask:0xf bound_ctrl:1
	v_cndmask_b32_e64 v83, v83, v114, s[0:1]
	v_cndmask_b32_e64 v82, v114, v82, s[0:1]
	v_cvt_pk_bf16_f32 v114, v82, v83
	v_readfirstlane_b32 s98, v158
	v_readfirstlane_b32 s99, v159
	v_and_b32_e32 v244, 30, v137
	v_lshlrev_b32_e32 v244, 1, v244
	v_lshl_add_u32 v244, v136, 11, v244
	s_lshl_b32 s100, s23, 11
	s_add_u32 s98, s98, s100
	s_addc_u32 s99, s99, 0
	s_add_u32 s100, s98, 0x800
	s_addc_u32 s101, s99, 0
	global_store_dword v244, v114, s[100:101] offset:-2048
	v_mov_b32_e32 v82, v84
	v_mfma_f32_32x32x16_bf16 v[50:65], v[186:189], v[110:113], v[50:65]
	v_cndmask_b32_e64 v83, v82, v85, s[0:1]
	s_add_i32 s8, s8, -1
	s_add_i32 s82, s82, 1
	v_mov_b32_dpp v83, v83 quad_perm:[1,0,3,2] row_mask:0xf bank_mask:0xf bound_ctrl:1
	v_cndmask_b32_e64 v84, v85, v83, s[0:1]
	v_cndmask_b32_e64 v82, v83, v82, s[0:1]
	v_cvt_pk_bf16_f32 v84, v82, v84
	global_store_dword v244, v84, s[100:101] offset:2048
	v_mov_b32_e32 v82, v86
	v_mfma_f32_32x32x16_bf16 v[34:49], v[190:193], v[106:109], v[34:49]
	v_cndmask_b32_e64 v83, v82, v87, s[0:1]
	s_nop 1
	v_mov_b32_dpp v83, v83 quad_perm:[1,0,3,2] row_mask:0xf bank_mask:0xf bound_ctrl:1
	v_cndmask_b32_e64 v84, v87, v83, s[0:1]
	v_cndmask_b32_e64 v82, v83, v82, s[0:1]
	v_cvt_pk_bf16_f32 v84, v82, v84
	s_add_u32 s100, s98, 0x4800
	s_addc_u32 s101, s99, 0
	global_store_dword v244, v84, s[100:101] offset:-2048
	v_mov_b32_e32 v82, v89
	v_mfma_f32_32x32x16_bf16 v[50:65], v[194:197], v[106:109], v[50:65]
	v_cndmask_b32_e64 v83, v88, v82, s[0:1]
	s_nop 1
	v_mov_b32_dpp v83, v83 quad_perm:[1,0,3,2] row_mask:0xf bank_mask:0xf bound_ctrl:1
	v_cndmask_b32_e64 v82, v82, v83, s[0:1]
	v_cndmask_b32_e64 v83, v83, v88, s[0:1]
	v_cvt_pk_bf16_f32 v84, v83, v82
	global_store_dword v244, v84, s[100:101] offset:2048
	v_mov_b32_e32 v82, v90
	v_mfma_f32_32x32x16_bf16 v[34:49], v[204:207], v[102:105], v[34:49]
	v_cndmask_b32_e64 v83, v82, v91, s[0:1]
	s_nop 1
	v_mov_b32_dpp v83, v83 quad_perm:[1,0,3,2] row_mask:0xf bank_mask:0xf bound_ctrl:1
	v_cndmask_b32_e64 v84, v91, v83, s[0:1]
	v_cndmask_b32_e64 v82, v83, v82, s[0:1]
	v_cvt_pk_bf16_f32 v84, v82, v84
	s_add_u32 s100, s98, 0x8800
	s_addc_u32 s101, s99, 0
	global_store_dword v244, v84, s[100:101] offset:-2048
	v_mov_b32_e32 v82, v92
	v_mfma_f32_32x32x16_bf16 v[50:65], v[208:211], v[102:105], v[50:65]
	v_cndmask_b32_e64 v83, v82, v93, s[0:1]
	s_nop 1
	v_mov_b32_dpp v83, v83 quad_perm:[1,0,3,2] row_mask:0xf bank_mask:0xf bound_ctrl:1
	v_cndmask_b32_e64 v84, v93, v83, s[0:1]
	v_cndmask_b32_e64 v82, v83, v82, s[0:1]
	v_cvt_pk_bf16_f32 v84, v82, v84
	global_store_dword v244, v84, s[100:101] offset:2048
	v_mov_b32_e32 v82, v95
	v_mfma_f32_32x32x16_bf16 v[34:49], v[224:227], v[98:101], v[34:49]
	v_cndmask_b32_e64 v83, v94, v82, s[0:1]
	s_nop 1
	v_mov_b32_dpp v83, v83 quad_perm:[1,0,3,2] row_mask:0xf bank_mask:0xf bound_ctrl:1
	v_cndmask_b32_e64 v82, v82, v83, s[0:1]
	v_cndmask_b32_e64 v83, v83, v94, s[0:1]
	v_cvt_pk_bf16_f32 v84, v83, v82
	s_add_u32 s100, s98, 0xc800
	s_addc_u32 s101, s99, 0
	global_store_dword v244, v84, s[100:101] offset:-2048
	v_mov_b32_e32 v82, v96
	v_mfma_f32_32x32x16_bf16 v[50:65], v[228:231], v[98:101], v[50:65]
	v_cndmask_b32_e64 v83, v82, v97, s[0:1]
	s_nop 1
	v_mov_b32_dpp v83, v83 quad_perm:[1,0,3,2] row_mask:0xf bank_mask:0xf bound_ctrl:1
	v_cndmask_b32_e64 v84, v97, v83, s[0:1]
	v_cndmask_b32_e64 v82, v83, v82, s[0:1]
	v_cvt_pk_bf16_f32 v84, v82, v84
	global_store_dword v244, v84, s[100:101] offset:2048
	s_or_b32 s23, s23, 32
	v_cndmask_b32_e64 v82, v66, v67, s[0:1]
	s_nop 0
	v_mov_b32_dpp v82, v82 quad_perm:[1,0,3,2] row_mask:0xf bank_mask:0xf bound_ctrl:1
	v_cndmask_b32_e64 v67, v67, v82, s[0:1]
	v_cndmask_b32_e64 v66, v82, v66, s[0:1]
	v_cvt_pk_bf16_f32 v82, v66, v67
	s_add_u32 s100, s98, 0x10800
	s_addc_u32 s101, s99, 0
	global_store_dword v244, v82, s[100:101] offset:-2048
	v_mov_b32_e32 v66, v69
	s_nop 0
	v_cndmask_b32_e64 v67, v68, v66, s[0:1]
	s_nop 1
	v_mov_b32_dpp v67, v67 quad_perm:[1,0,3,2] row_mask:0xf bank_mask:0xf bound_ctrl:1
	v_cndmask_b32_e64 v66, v66, v67, s[0:1]
	v_cndmask_b32_e64 v67, v67, v68, s[0:1]
	v_cvt_pk_bf16_f32 v68, v67, v66
	global_store_dword v244, v68, s[100:101] offset:2048
	v_mov_b32_e32 v66, v70
	s_nop 0
	v_cndmask_b32_e64 v67, v66, v71, s[0:1]
	s_nop 1
	v_mov_b32_dpp v67, v67 quad_perm:[1,0,3,2] row_mask:0xf bank_mask:0xf bound_ctrl:1
	v_cndmask_b32_e64 v68, v71, v67, s[0:1]
	v_cndmask_b32_e64 v66, v67, v66, s[0:1]
	v_cvt_pk_bf16_f32 v68, v66, v68
	s_add_u32 s100, s98, 0x14800
	s_addc_u32 s101, s99, 0
	global_store_dword v244, v68, s[100:101] offset:-2048
; #define LAS __attribute__((address_space(3)))
; DI int crow(int r, int hi) { return (r & 3) + 8 * (r >> 2) + 4 * hi; }
; DI unsigned pkbf(float a, float b) { f32x2 v = {a, b}; bfx2 r = __builtin_convertvector(v, bfx2); return __builtin_bit_cast(unsigned, r); }
; DI void phase_gla_chain(const Params& P, int l, int task0, int ntask_stride, LAS unsigned char* lds) {
;     ...
;         __syncthreads();
;         CH_ISSUE(0, 0);
;         for (int n = 0; n < 64; ++n) {
;             const int b = n & 1;
;             if (n == 0) asm volatile("s_waitcnt vmcnt(0)" ::: "memory"); else asm volatile("s_waitcnt vmcnt(16)" ::: "memory");
;             __builtin_amdgcn_s_barrier();
;             asm volatile("" ::: "memory");
;             if (n + 1 < 64) CH_ISSUE(n + 1, b ^ 1);
;             const LAS unsigned char* B = lds + b * CH_BUF;
;             const int i0 = r32, i1 = 32 + r32; const int vv = wid * 32 + r32;
;             bf16x8 fa[8], fb[8], vf[4];
;             f32x16 o[2]; for (int x = 0; x < 16; ++x) { o[0][x] = 0.f; o[1][x] = 0.f; }
;     ...
;             RD_QD(fa, 0);
; #pragma unroll
;             for (int ks = 0; ks < 4; ++ks) vf[ks] = *(const LAS bf16x8*)(B + CH_VT + vv * 128 + (((2 * ks + hi) ^ ((vv >> 1) & 7)) << 4));
;             __builtin_amdgcn_sched_barrier(0);
;             RD_QD(fb, 4);
;     ...
;             { const int cs = dir ? 63 - n : n; const size_t tokb = (size_t)sq * SEQL + cs * 64; const int odd = lane & 1;
;               bf16_t* ob = OFB + (size_t)dir * MTOK * 1024 + h * 256 + wid * 32 + (r32 & ~1);
; #pragma unroll
;               for (int ib = 0; ib < 2; ++ib)
; #pragma unroll
;                   for (int x = 0; x < 16; x += 2) { float ea_ = o[ib][x], eb_ = o[ib][x + 1]; asm volatile("" : "+v"(ea_), "+v"(eb_)); const float mine = odd ? eb_ : ea_, give = odd ? ea_ : eb_;
;                       const float got = __int_as_float(__builtin_amdgcn_update_dpp(0, __float_as_int(give), 0xB1, 0xF, 0xF, true));
;                       const unsigned w = odd ? pkbf(got, mine) : pkbf(mine, got);
;                       *(unsigned*)(ob + (tokb + ib * 32 + crow(x + odd, hi)) * 1024) = w; } }
	v_mov_b32_e32 v66, v72
	s_nop 0
	v_cndmask_b32_e64 v67, v66, v73, s[0:1]
	s_nop 1
	v_mov_b32_dpp v67, v67 quad_perm:[1,0,3,2] row_mask:0xf bank_mask:0xf bound_ctrl:1
	v_cndmask_b32_e64 v68, v73, v67, s[0:1]
	v_cndmask_b32_e64 v66, v67, v66, s[0:1]
	v_cvt_pk_bf16_f32 v68, v66, v68
	global_store_dword v244, v68, s[100:101] offset:2048
	v_mov_b32_e32 v66, v75
	s_nop 0
	v_cndmask_b32_e64 v67, v74, v66, s[0:1]
	s_nop 1
	v_mov_b32_dpp v67, v67 quad_perm:[1,0,3,2] row_mask:0xf bank_mask:0xf bound_ctrl:1
	v_cndmask_b32_e64 v66, v66, v67, s[0:1]
	v_cndmask_b32_e64 v67, v67, v74, s[0:1]
	v_cvt_pk_bf16_f32 v68, v67, v66
	s_add_u32 s100, s98, 0x18800
	s_addc_u32 s101, s99, 0
	global_store_dword v244, v68, s[100:101] offset:-2048
	v_mov_b32_e32 v66, v77
	s_nop 0
	v_cndmask_b32_e64 v67, v76, v66, s[0:1]
	s_nop 1
	v_mov_b32_dpp v67, v67 quad_perm:[1,0,3,2] row_mask:0xf bank_mask:0xf bound_ctrl:1
	v_cndmask_b32_e64 v66, v66, v67, s[0:1]
	v_cndmask_b32_e64 v67, v67, v76, s[0:1]
	v_cvt_pk_bf16_f32 v68, v67, v66
	global_store_dword v244, v68, s[100:101] offset:2048
	v_mov_b32_e32 v66, v78
	s_nop 0
	v_cndmask_b32_e64 v67, v66, v79, s[0:1]
	s_nop 1
	v_mov_b32_dpp v67, v67 quad_perm:[1,0,3,2] row_mask:0xf bank_mask:0xf bound_ctrl:1
	v_cndmask_b32_e64 v68, v79, v67, s[0:1]
	v_cndmask_b32_e64 v66, v67, v66, s[0:1]
	v_cvt_pk_bf16_f32 v68, v66, v68
	s_add_u32 s100, s98, 0x1c800
	s_addc_u32 s101, s99, 0
	global_store_dword v244, v68, s[100:101] offset:-2048
	v_mov_b32_e32 v66, v81
	s_nop 0
	v_cndmask_b32_e64 v67, v80, v66, s[0:1]
	s_nop 1
	v_mov_b32_dpp v67, v67 quad_perm:[1,0,3,2] row_mask:0xf bank_mask:0xf bound_ctrl:1
	v_cndmask_b32_e64 v66, v66, v67, s[0:1]
	v_cndmask_b32_e64 v67, v67, v80, s[0:1]
	v_cvt_pk_bf16_f32 v68, v67, v66
	global_store_dword v244, v68, s[100:101] offset:2048
	s_cmp_eq_u32 s8, -2
	s_cbranch_scc1 .LBB0_965
.LBB0_972:
	s_add_i32 s83, s82, -1
	s_waitcnt vmcnt(16)
	s_barrier
	s_and_b32 s84, s83, 1
	s_mul_i32 s84, s84, 0x12400
	s_add_i32 s22, s84, 0
	v_add_u32_e32 v74, s22, v201
	v_add_u32_e32 v75, s22, v141
	v_add_u32_e32 v66, v74, v149
	v_add_u32_e32 v70, v75, v149
	v_add_u32_e32 v76, v74, v151
	ds_read_b128 v[66:69], v66
	ds_read_b128 v[70:73], v70
	v_add_u32_e32 v77, v75, v151
	ds_read_b128 v[182:185], v76
	ds_read_b128 v[186:189], v77
	v_add_u32_e32 v76, v74, v153
	v_add_u32_e32 v77, v75, v153
	ds_read_b128 v[190:193], v76
	ds_read_b128 v[194:197], v77
	v_add_u32_e32 v76, v74, v160
	v_add_u32_e32 v77, v75, v160
	ds_read_b128 v[204:207], v76
	ds_read_b128 v[208:211], v77
	v_add_u32_e32 v76, s22, v173
	v_add_u32_e32 v77, v76, v162
	v_add_u32_e32 v78, v76, v164
	ds_read_b128 v[110:113], v77 offset:40960
	ds_read_b128 v[106:109], v78 offset:40960
	v_add_u32_e32 v77, v76, v165
	v_add_u32_e32 v76, v76, v166
	ds_read_b128 v[102:105], v77 offset:40960
	ds_read_b128 v[98:101], v76 offset:40960
	v_add_u32_e32 v76, v74, v167
	v_add_u32_e32 v77, v75, v167
	ds_read_b128 v[212:215], v76
	ds_read_b128 v[216:219], v77
	v_add_u32_e32 v76, v74, v168
	v_add_u32_e32 v77, v75, v168
	ds_read_b128 v[220:223], v76
	ds_read_b128 v[130:133], v77
	v_add_u32_e32 v76, v74, v169
	v_add_u32_e32 v74, v74, v170
	v_add_u32_e32 v77, v75, v169
	ds_read_b128 v[126:129], v76
	ds_read_b128 v[122:125], v77
	v_add_u32_e32 v75, v75, v170
	ds_read_b128 v[118:121], v74
	ds_read_b128 v[114:117], v75
	v_cvt_pk_bf16_f32 v74, v2, v3
	v_cvt_pk_bf16_f32 v75, v4, v5
	v_cvt_pk_bf16_f32 v76, v6, v7
	v_cvt_pk_bf16_f32 v77, v8, v9
	v_cvt_pk_bf16_f32 v224, v10, v11
	v_cvt_pk_bf16_f32 v225, v12, v13
	s_cmp_eq_u32 s8, -1
	s_cbranch_scc1 .LBB0_971
	s_and_b64 s[22:23], s[10:11], exec
	s_cselect_b32 s22, s82, s8
	s_add_i32 s22, s22, s81
	s_lshl_b32 s22, s22, 2
	s_or_b32 s86, s22, s80
	s_ashr_i32 s87, s86, 31
	s_add_u32 s22, s25, s86
	s_addc_u32 s23, 0, s87
	s_mul_i32 s64, s23, 0xa000
	s_mul_hi_u32 s65, s22, 0xa000
	s_add_i32 s65, s65, s64
	s_mul_i32 s64, s22, 0xa000
	s_add_u32 s64, s27, s64
	s_addc_u32 s65, s28, s65
	s_lshl_b64 s[86:87], s[86:87], 15
	s_add_u32 s66, s29, s86
	s_addc_u32 s67, s30, s87
	s_sub_i32 s68, 0x12400, s84
	s_add_i32 s85, s68, 0
	v_add_u32_e32 v245, 0x400, v134
	v_add_u32_e32 v246, 0x800, v134
	v_add_u32_e32 v247, 0xc00, v134
	v_add_u32_e32 v248, 0x1000, v134
	s_lshl_b32 s32, s31, 4
	s_lshl_b32 s98, s31, 2
	s_add_i32 s98, s98, s32
	s_add_u32 s100, s64, s98
	s_addc_u32 s101, s65, 0
	s_add_i32 s99, s85, s98
	s_add_i32 m0, s99, 0x0
	s_nop 0
	global_load_lds_dwordx4 v134, s[100:101] nt
	s_add_i32 m0, s99, 0x400
	s_nop 0
	global_load_lds_dwordx4 v245, s[100:101] nt
	s_add_i32 m0, s99, 0x800
	s_nop 0
	global_load_lds_dwordx4 v246, s[100:101] nt
	s_add_i32 m0, s99, 0xc00
	s_nop 0
	global_load_lds_dwordx4 v247, s[100:101] nt
	s_add_i32 m0, s99, 0x1000
	s_nop 0
	global_load_lds_dwordx4 v248, s[100:101] nt
	s_add_u32 s100, s66, s32
	s_addc_u32 s101, s67, 0
	s_add_i32 s99, s85, s32
	s_add_i32 m0, s99, 0xa000
	s_nop 0
	global_load_lds_dwordx4 v134, s[100:101] nt
	s_add_i32 m0, s99, 0xa400
	s_nop 0
	global_load_lds_dwordx4 v245, s[100:101] nt
	s_add_i32 m0, s99, 0xa800
	s_nop 0
	global_load_lds_dwordx4 v246, s[100:101] nt
	s_add_i32 m0, s99, 0xac00
	s_nop 0
	global_load_lds_dwordx4 v247, s[100:101] nt
	s_cmp_lg_u64 s[2:3], 0
	s_cbranch_scc1 .Lchain_nodec_1
	s_lshl_b64 s[100:101], s[22:23], 9
	s_add_i32 s98, s85, s31
	s_add_i32 m0, s98, 0x12000
	v_lshl_add_u64 v[250:251], v[156:157], 0, s[100:101]
	global_load_lds_dword v[250:251], off
.Lchain_nodec_1:
	s_add_i32 s22, s84, 0
	s_branch .LBB0_971
